# GEMM1 K-loop: load segments (ds_read + LDS-DMA issue) run at s_setprio 2, MFMA clusters stay at prio 1
# baseline (speedup 1.0000x reference)
.LBB0_312:
	s_setprio 2
	s_add_u32 s4, s0, 0xfff80080
	s_addc_u32 s5, s1, -1
	s_add_i32 s54, 0, 0x10000
	s_cmp_eq_u32 s53, 28
	s_cselect_b32 s17, s37, s5
	s_cselect_b32 s16, s45, s4
	s_cselect_b32 s5, s29, s52
	s_cselect_b32 s4, s50, s51
	s_add_i32 s56, 0, 0x14000
	v_add_u32_e32 v156, s54, v160
	v_add_u32_e32 v163, s56, v160
	ds_read_b128 v[144:147], v156
	ds_read_b128 v[148:151], v156 offset:1024
	ds_read_b128 v[152:155], v156 offset:2048
	ds_read_b128 v[156:159], v156 offset:3072
	ds_read_b128 v[164:167], v163
	ds_read_b128 v[168:171], v163 offset:1024
	ds_read_b128 v[172:175], v163 offset:2048
	ds_read_b128 v[176:179], v163 offset:3072
	v_lshl_add_u64 v[238:239], s[0:1], 0, v[140:141]
	s_add_i32 m0, s22, 0xc000
	ds_read_b128 v[180:183], v162
	ds_read_b128 v[184:187], v162 offset:1024
	ds_read_b128 v[188:191], v162 offset:2048
	ds_read_b128 v[192:195], v162 offset:3072
	ds_read_b128 v[204:207], v162 offset:4096
	ds_read_b128 v[208:211], v162 offset:5120
	ds_read_b128 v[212:215], v162 offset:6144
	ds_read_b128 v[216:219], v162 offset:7168
	global_load_lds_dwordx4 v[238:239], off
	v_lshl_add_u64 v[238:239], s[0:1], 0, v[142:143]
	s_add_i32 m0, s22, 0xe000
	s_nop 0
	global_load_lds_dwordx4 v[238:239], off
	s_waitcnt vmcnt(8)
	s_waitcnt lgkmcnt(0)
	s_barrier
	s_setprio 1
	s_waitcnt lgkmcnt(0)
	v_mfma_f32_16x16x32_bf16 v[126:129], v[144:147], v[180:183], v[126:129]
	v_mfma_f32_16x16x32_bf16 v[122:125], v[152:155], v[180:183], v[122:125]
	v_mfma_f32_16x16x32_bf16 v[114:117], v[144:147], v[188:191], v[114:117]
	v_mfma_f32_16x16x32_bf16 v[106:109], v[152:155], v[188:191], v[106:109]
	v_mfma_f32_16x16x32_bf16 v[102:105], v[144:147], v[204:207], v[102:105]
	v_mfma_f32_16x16x32_bf16 v[94:97], v[152:155], v[204:207], v[94:97]
	v_mfma_f32_16x16x32_bf16 v[86:89], v[144:147], v[212:215], v[86:89]
	v_mfma_f32_16x16x32_bf16 v[78:81], v[152:155], v[212:215], v[78:81]
	v_mfma_f32_16x16x32_bf16 v[126:129], v[148:151], v[184:187], v[126:129]
	v_mfma_f32_16x16x32_bf16 v[122:125], v[156:159], v[184:187], v[122:125]
	v_mfma_f32_16x16x32_bf16 v[114:117], v[148:151], v[192:195], v[114:117]
	v_mfma_f32_16x16x32_bf16 v[106:109], v[156:159], v[192:195], v[106:109]
	v_mfma_f32_16x16x32_bf16 v[102:105], v[148:151], v[208:211], v[102:105]
	v_mfma_f32_16x16x32_bf16 v[94:97], v[156:159], v[208:211], v[94:97]
	v_mfma_f32_16x16x32_bf16 v[86:89], v[148:151], v[216:219], v[86:89]
	v_mfma_f32_16x16x32_bf16 v[78:81], v[156:159], v[216:219], v[78:81]
	s_setprio 0
	s_setprio 1
	v_mfma_f32_16x16x32_bf16 v[118:121], v[164:167], v[180:183], v[118:121]
	v_mfma_f32_16x16x32_bf16 v[110:113], v[172:175], v[180:183], v[110:113]
	v_mfma_f32_16x16x32_bf16 v[98:101], v[164:167], v[188:191], v[98:101]
	v_mfma_f32_16x16x32_bf16 v[90:93], v[172:175], v[188:191], v[90:93]
	v_mfma_f32_16x16x32_bf16 v[82:85], v[164:167], v[204:207], v[82:85]
	v_mfma_f32_16x16x32_bf16 v[74:77], v[172:175], v[204:207], v[74:77]
	v_mfma_f32_16x16x32_bf16 v[70:73], v[164:167], v[212:215], v[70:73]
	v_mfma_f32_16x16x32_bf16 v[66:69], v[172:175], v[212:215], v[66:69]
	v_mfma_f32_16x16x32_bf16 v[118:121], v[168:171], v[184:187], v[118:121]
	v_mfma_f32_16x16x32_bf16 v[110:113], v[176:179], v[184:187], v[110:113]
	v_mfma_f32_16x16x32_bf16 v[98:101], v[168:171], v[192:195], v[98:101]
	v_mfma_f32_16x16x32_bf16 v[90:93], v[176:179], v[192:195], v[90:93]
	v_mfma_f32_16x16x32_bf16 v[82:85], v[168:171], v[208:211], v[82:85]
	v_mfma_f32_16x16x32_bf16 v[74:77], v[176:179], v[208:211], v[74:77]
	v_mfma_f32_16x16x32_bf16 v[70:73], v[168:171], v[216:219], v[70:73]
	v_mfma_f32_16x16x32_bf16 v[66:69], v[176:179], v[216:219], v[66:69]
	s_setprio 0
	s_barrier
	s_setprio 2
	s_add_i32 s54, s54, s19
	v_lshl_add_u64 v[238:239], s[4:5], 0, v[134:135]
	s_mov_b32 m0, s54
	ds_read_b128 v[180:183], v162 offset:16384
	ds_read_b128 v[184:187], v162 offset:17408
	ds_read_b128 v[188:191], v162 offset:18432
	ds_read_b128 v[192:195], v162 offset:19456
	ds_read_b128 v[204:207], v162 offset:20480
	ds_read_b128 v[208:211], v162 offset:21504
	ds_read_b128 v[212:215], v162 offset:22528
	ds_read_b128 v[216:219], v162 offset:23552
	global_load_lds_dwordx4 v[238:239], off
	s_add_i32 m0, s54, 0x2000
	s_add_u32 s54, s4, 0x80000
	v_lshl_add_u64 v[240:241], s[4:5], 0, v[130:131]
	s_addc_u32 s55, s5, 0
	s_add_i32 s56, s56, s19
	global_load_lds_dwordx4 v[240:241], off
	v_lshl_add_u64 v[242:243], s[54:55], 0, v[134:135]
	s_mov_b32 m0, s56
	v_lshl_add_u64 v[244:245], s[16:17], 0, v[132:133]
	global_load_lds_dwordx4 v[242:243], off
	v_lshl_add_u64 v[242:243], s[54:55], 0, v[130:131]
	s_add_i32 m0, s56, 0x2000
	s_nop 0
	global_load_lds_dwordx4 v[242:243], off
	v_lshl_add_u64 v[242:243], s[16:17], 0, v[136:137]
	s_mov_b32 m0, s22
	s_nop 0
	global_load_lds_dwordx4 v[242:243], off
	s_mov_b32 m0, s23
	s_nop 0
	global_load_lds_dwordx4 v[244:245], off
	s_waitcnt vmcnt(8)
	s_waitcnt lgkmcnt(0)
	s_barrier
	s_setprio 1
	s_waitcnt lgkmcnt(0)
	v_mfma_f32_16x16x32_bf16 v[62:65], v[144:147], v[180:183], v[62:65]
	v_mfma_f32_16x16x32_bf16 v[58:61], v[152:155], v[180:183], v[58:61]
	v_mfma_f32_16x16x32_bf16 v[54:57], v[144:147], v[188:191], v[54:57]
	v_mfma_f32_16x16x32_bf16 v[46:49], v[152:155], v[188:191], v[46:49]
	v_mfma_f32_16x16x32_bf16 v[38:41], v[144:147], v[204:207], v[38:41]
	v_mfma_f32_16x16x32_bf16 v[30:33], v[152:155], v[204:207], v[30:33]
	v_mfma_f32_16x16x32_bf16 v[22:25], v[144:147], v[212:215], v[22:25]
	v_mfma_f32_16x16x32_bf16 v[14:17], v[152:155], v[212:215], v[14:17]
	v_mfma_f32_16x16x32_bf16 v[62:65], v[148:151], v[184:187], v[62:65]
	v_mfma_f32_16x16x32_bf16 v[58:61], v[156:159], v[184:187], v[58:61]
	v_mfma_f32_16x16x32_bf16 v[54:57], v[148:151], v[192:195], v[54:57]
	v_mfma_f32_16x16x32_bf16 v[46:49], v[156:159], v[192:195], v[46:49]
	v_mfma_f32_16x16x32_bf16 v[38:41], v[148:151], v[208:211], v[38:41]
	v_mfma_f32_16x16x32_bf16 v[30:33], v[156:159], v[208:211], v[30:33]
	v_mfma_f32_16x16x32_bf16 v[22:25], v[148:151], v[216:219], v[22:25]
	v_mfma_f32_16x16x32_bf16 v[14:17], v[156:159], v[216:219], v[14:17]
	s_setprio 0
	s_setprio 1
	v_mfma_f32_16x16x32_bf16 v[50:53], v[164:167], v[180:183], v[50:53]
	v_mfma_f32_16x16x32_bf16 v[42:45], v[172:175], v[180:183], v[42:45]
	v_mfma_f32_16x16x32_bf16 v[34:37], v[164:167], v[188:191], v[34:37]
	v_mfma_f32_16x16x32_bf16 v[26:29], v[172:175], v[188:191], v[26:29]
	v_mfma_f32_16x16x32_bf16 v[18:21], v[164:167], v[204:207], v[18:21]
	v_mfma_f32_16x16x32_bf16 v[10:13], v[172:175], v[204:207], v[10:13]
	v_mfma_f32_16x16x32_bf16 v[6:9], v[164:167], v[212:215], v[6:9]
	v_mfma_f32_16x16x32_bf16 v[2:5], v[172:175], v[212:215], v[2:5]
	v_mfma_f32_16x16x32_bf16 v[50:53], v[168:171], v[184:187], v[50:53]
	v_mfma_f32_16x16x32_bf16 v[42:45], v[176:179], v[184:187], v[42:45]
	v_mfma_f32_16x16x32_bf16 v[34:37], v[168:171], v[192:195], v[34:37]
	v_mfma_f32_16x16x32_bf16 v[26:29], v[176:179], v[192:195], v[26:29]
	v_mfma_f32_16x16x32_bf16 v[18:21], v[168:171], v[208:211], v[18:21]
	v_mfma_f32_16x16x32_bf16 v[10:13], v[176:179], v[208:211], v[10:13]
	v_mfma_f32_16x16x32_bf16 v[6:9], v[168:171], v[216:219], v[6:9]
	v_mfma_f32_16x16x32_bf16 v[2:5], v[176:179], v[216:219], v[2:5]
	s_setprio 0
	s_barrier
	s_setprio 2
	s_add_i32 s54, 0, 0x18000
	s_add_i32 s55, 0, 0x1c000
	v_add_u32_e32 v156, s54, v160
	v_add_u32_e32 v163, s55, v160
	ds_read_b128 v[144:147], v156
	ds_read_b128 v[148:151], v156 offset:1024
	ds_read_b128 v[152:155], v156 offset:2048
	ds_read_b128 v[156:159], v156 offset:3072
	ds_read_b128 v[164:167], v163
	ds_read_b128 v[168:171], v163 offset:1024
	ds_read_b128 v[172:175], v163 offset:2048
	ds_read_b128 v[176:179], v163 offset:3072
	s_add_u32 s16, s16, 0x80000
	s_addc_u32 s17, s17, 0
	s_mov_b32 m0, s24
	v_lshl_add_u64 v[246:247], s[16:17], 0, v[136:137]
	ds_read_b128 v[180:183], v162 offset:32768
	ds_read_b128 v[184:187], v162 offset:33792
	ds_read_b128 v[188:191], v162 offset:34816
	ds_read_b128 v[192:195], v162 offset:35840
	ds_read_b128 v[204:207], v162 offset:36864
	ds_read_b128 v[208:211], v162 offset:37888
	ds_read_b128 v[212:215], v162 offset:38912
	ds_read_b128 v[216:219], v162 offset:39936
	global_load_lds_dwordx4 v[246:247], off
	v_lshl_add_u64 v[246:247], s[16:17], 0, v[132:133]
	s_mov_b32 m0, s25
	s_nop 0
	global_load_lds_dwordx4 v[246:247], off
	s_waitcnt vmcnt(8)
	s_waitcnt lgkmcnt(0)
	s_barrier
	s_setprio 1
	s_waitcnt lgkmcnt(0)
	v_mfma_f32_16x16x32_bf16 v[126:129], v[144:147], v[180:183], v[126:129]
	v_mfma_f32_16x16x32_bf16 v[122:125], v[152:155], v[180:183], v[122:125]
	v_mfma_f32_16x16x32_bf16 v[114:117], v[144:147], v[188:191], v[114:117]
	v_mfma_f32_16x16x32_bf16 v[106:109], v[152:155], v[188:191], v[106:109]
	v_mfma_f32_16x16x32_bf16 v[102:105], v[144:147], v[204:207], v[102:105]
	v_mfma_f32_16x16x32_bf16 v[94:97], v[152:155], v[204:207], v[94:97]
	v_mfma_f32_16x16x32_bf16 v[86:89], v[144:147], v[212:215], v[86:89]
	v_mfma_f32_16x16x32_bf16 v[78:81], v[152:155], v[212:215], v[78:81]
	v_mfma_f32_16x16x32_bf16 v[126:129], v[148:151], v[184:187], v[126:129]
	v_mfma_f32_16x16x32_bf16 v[122:125], v[156:159], v[184:187], v[122:125]
	v_mfma_f32_16x16x32_bf16 v[114:117], v[148:151], v[192:195], v[114:117]
	v_mfma_f32_16x16x32_bf16 v[106:109], v[156:159], v[192:195], v[106:109]
	v_mfma_f32_16x16x32_bf16 v[102:105], v[148:151], v[208:211], v[102:105]
	v_mfma_f32_16x16x32_bf16 v[94:97], v[156:159], v[208:211], v[94:97]
	v_mfma_f32_16x16x32_bf16 v[86:89], v[148:151], v[216:219], v[86:89]
	v_mfma_f32_16x16x32_bf16 v[78:81], v[156:159], v[216:219], v[78:81]
	s_setprio 0
	s_setprio 1
	v_mfma_f32_16x16x32_bf16 v[118:121], v[164:167], v[180:183], v[118:121]
	v_mfma_f32_16x16x32_bf16 v[110:113], v[172:175], v[180:183], v[110:113]
	v_mfma_f32_16x16x32_bf16 v[98:101], v[164:167], v[188:191], v[98:101]
	v_mfma_f32_16x16x32_bf16 v[90:93], v[172:175], v[188:191], v[90:93]
	v_mfma_f32_16x16x32_bf16 v[82:85], v[164:167], v[204:207], v[82:85]
	v_mfma_f32_16x16x32_bf16 v[74:77], v[172:175], v[204:207], v[74:77]
	v_mfma_f32_16x16x32_bf16 v[70:73], v[164:167], v[212:215], v[70:73]
	v_mfma_f32_16x16x32_bf16 v[66:69], v[172:175], v[212:215], v[66:69]
	v_mfma_f32_16x16x32_bf16 v[118:121], v[168:171], v[184:187], v[118:121]
	v_mfma_f32_16x16x32_bf16 v[110:113], v[176:179], v[184:187], v[110:113]
	v_mfma_f32_16x16x32_bf16 v[98:101], v[168:171], v[192:195], v[98:101]
	v_mfma_f32_16x16x32_bf16 v[90:93], v[176:179], v[192:195], v[90:93]
	v_mfma_f32_16x16x32_bf16 v[82:85], v[168:171], v[208:211], v[82:85]
	v_mfma_f32_16x16x32_bf16 v[74:77], v[176:179], v[208:211], v[74:77]
	v_mfma_f32_16x16x32_bf16 v[70:73], v[168:171], v[216:219], v[70:73]
	v_mfma_f32_16x16x32_bf16 v[66:69], v[176:179], v[216:219], v[66:69]
	s_setprio 0
	s_barrier
	s_setprio 2
	s_add_i32 s16, s54, s19
	v_lshl_add_u64 v[238:239], v[238:239], 0, s[30:31]
	s_mov_b32 m0, s16
	ds_read_b128 v[180:183], v162 offset:49152
	ds_read_b128 v[184:187], v162 offset:50176
	ds_read_b128 v[188:191], v162 offset:51200
	ds_read_b128 v[192:195], v162 offset:52224
	ds_read_b128 v[204:207], v162 offset:53248
	ds_read_b128 v[208:211], v162 offset:54272
	ds_read_b128 v[212:215], v162 offset:55296
	ds_read_b128 v[216:219], v162 offset:56320
	global_load_lds_dwordx4 v[238:239], off
	s_add_i32 m0, s16, 0x2000
	s_add_u32 s4, s4, 0x80080
	v_lshl_add_u64 v[238:239], v[240:241], 0, s[30:31]
	s_addc_u32 s5, s5, 0
	s_add_i32 s16, s55, s19
	global_load_lds_dwordx4 v[238:239], off
	v_lshl_add_u64 v[238:239], s[4:5], 0, v[134:135]
	s_mov_b32 m0, s16
	s_nop 0
	global_load_lds_dwordx4 v[238:239], off
	v_lshl_add_u64 v[238:239], s[4:5], 0, v[130:131]
	s_add_i32 m0, s16, 0x2000
	s_nop 0
	global_load_lds_dwordx4 v[238:239], off
	v_lshl_add_u64 v[238:239], v[242:243], 0, s[30:31]
	s_mov_b32 m0, s47
	s_nop 0
	global_load_lds_dwordx4 v[238:239], off
	v_lshl_add_u64 v[238:239], v[244:245], 0, s[30:31]
	s_mov_b32 m0, s48
	s_nop 0
	global_load_lds_dwordx4 v[238:239], off
	s_waitcnt vmcnt(8)
	s_waitcnt lgkmcnt(0)
	s_barrier
	s_setprio 1
	s_waitcnt lgkmcnt(0)
	v_mfma_f32_16x16x32_bf16 v[62:65], v[144:147], v[180:183], v[62:65]
	v_mfma_f32_16x16x32_bf16 v[58:61], v[152:155], v[180:183], v[58:61]
	v_mfma_f32_16x16x32_bf16 v[54:57], v[144:147], v[188:191], v[54:57]
	v_mfma_f32_16x16x32_bf16 v[46:49], v[152:155], v[188:191], v[46:49]
	v_mfma_f32_16x16x32_bf16 v[38:41], v[144:147], v[204:207], v[38:41]
	v_mfma_f32_16x16x32_bf16 v[30:33], v[152:155], v[204:207], v[30:33]
	v_mfma_f32_16x16x32_bf16 v[22:25], v[144:147], v[212:215], v[22:25]
	v_mfma_f32_16x16x32_bf16 v[14:17], v[152:155], v[212:215], v[14:17]
	v_mfma_f32_16x16x32_bf16 v[62:65], v[148:151], v[184:187], v[62:65]
	v_mfma_f32_16x16x32_bf16 v[58:61], v[156:159], v[184:187], v[58:61]
	v_mfma_f32_16x16x32_bf16 v[54:57], v[148:151], v[192:195], v[54:57]
	v_mfma_f32_16x16x32_bf16 v[46:49], v[156:159], v[192:195], v[46:49]
	v_mfma_f32_16x16x32_bf16 v[38:41], v[148:151], v[208:211], v[38:41]
	v_mfma_f32_16x16x32_bf16 v[30:33], v[156:159], v[208:211], v[30:33]
	v_mfma_f32_16x16x32_bf16 v[22:25], v[148:151], v[216:219], v[22:25]
	v_mfma_f32_16x16x32_bf16 v[14:17], v[156:159], v[216:219], v[14:17]
	s_setprio 0
	s_setprio 1
	v_mfma_f32_16x16x32_bf16 v[50:53], v[164:167], v[180:183], v[50:53]
	v_mfma_f32_16x16x32_bf16 v[42:45], v[172:175], v[180:183], v[42:45]
	v_mfma_f32_16x16x32_bf16 v[34:37], v[164:167], v[188:191], v[34:37]
	v_mfma_f32_16x16x32_bf16 v[26:29], v[172:175], v[188:191], v[26:29]
	v_mfma_f32_16x16x32_bf16 v[18:21], v[164:167], v[204:207], v[18:21]
	v_mfma_f32_16x16x32_bf16 v[10:13], v[172:175], v[204:207], v[10:13]
	v_mfma_f32_16x16x32_bf16 v[6:9], v[164:167], v[212:215], v[6:9]
	v_mfma_f32_16x16x32_bf16 v[2:5], v[172:175], v[212:215], v[2:5]
	v_mfma_f32_16x16x32_bf16 v[50:53], v[168:171], v[184:187], v[50:53]
	v_mfma_f32_16x16x32_bf16 v[42:45], v[176:179], v[184:187], v[42:45]
	v_mfma_f32_16x16x32_bf16 v[34:37], v[168:171], v[192:195], v[34:37]
	v_mfma_f32_16x16x32_bf16 v[26:29], v[176:179], v[192:195], v[26:29]
	v_mfma_f32_16x16x32_bf16 v[18:21], v[168:171], v[208:211], v[18:21]
	v_mfma_f32_16x16x32_bf16 v[10:13], v[176:179], v[208:211], v[10:13]
	v_mfma_f32_16x16x32_bf16 v[6:9], v[168:171], v[216:219], v[6:9]
	v_mfma_f32_16x16x32_bf16 v[2:5], v[176:179], v[216:219], v[2:5]
	s_setprio 0
	s_barrier
	s_add_i32 s53, s53, 2
	s_add_u32 s0, s0, 0x100
	s_addc_u32 s1, s1, 0
	s_add_u32 s51, s51, 0x100
	s_addc_u32 s52, s52, 0
	s_cmp_gt_u32 s53, 29
	s_cbranch_scc0 .LBB0_312
	s_and_b64 vcc, exec, s[10:11]
	s_cbranch_vccz .LBB0_315
	s_barrier
